# phase-2 YB / MIX stores write-through (sc1)
# baseline (speedup 1.0000x reference)
.LBB0_444:
	s_add_i32 s4, s47, s28
	s_and_b32 s4, s4, 0xffffff80
	v_add_u32_e32 v118, s4, v125
	s_lshl_b32 s3, s51, 8
	v_ashrrev_i32_e32 v119, 31, v118
	v_or_b32_e32 v100, s3, v126
	v_lshlrev_b64 v[136:137], 12, v[118:119]
	v_lshl_add_u64 v[136:137], s[58:59], 0, v[136:137]
	v_lshlrev_b32_e32 v100, 1, v100
	v_lshl_add_u64 v[136:137], v[136:137], 0, v[100:101]
	s_mov_b64 s[80:81], 0x10000
	s_mov_b64 s[82:83], 0x20000
	s_mov_b64 s[86:87], 0x30000
	v_lshl_add_u64 v[190:191], v[136:137], 0, s[80:81]
	v_lshl_add_u64 v[192:193], v[136:137], 0, s[82:83]
	v_lshl_add_u64 v[194:195], v[136:137], 0, s[86:87]
	global_load_dwordx2 v[138:139], v[136:137], off
	global_load_dwordx2 v[152:153], v[136:137], off offset:32
	global_load_dwordx2 v[156:157], v[136:137], off offset:64
	s_nop 0
	global_load_dwordx2 v[136:137], v[136:137], off offset:96
	global_load_dwordx2 v[196:197], v[190:191], off
	global_load_dwordx2 v[198:199], v[190:191], off offset:32
	global_load_dwordx2 v[200:201], v[190:191], off offset:64
	global_load_dwordx2 v[202:203], v[190:191], off offset:96
	global_load_dwordx2 v[204:205], v[192:193], off
	global_load_dwordx2 v[206:207], v[192:193], off offset:32
	global_load_dwordx2 v[208:209], v[192:193], off offset:64
	global_load_dwordx2 v[226:227], v[192:193], off offset:96
	global_load_dwordx2 v[228:229], v[194:195], off
	global_load_dwordx2 v[230:231], v[194:195], off offset:32
	global_load_dwordx2 v[232:233], v[194:195], off offset:64
	global_load_dwordx2 v[234:235], v[194:195], off offset:96
	s_waitcnt vmcnt(19)
	v_add_f32_e32 v158, v113, v80
	v_or_b32_e32 v80, 16, v118
	v_add_f32_e32 v92, v113, v92
	v_add_f32_e32 v93, v113, v93
	v_add_f32_e32 v94, v113, v94
	v_add_f32_e32 v95, v113, v95
	v_add_f32_e32 v88, v113, v88
	v_add_f32_e32 v89, v113, v89
	v_add_f32_e32 v90, v113, v90
	v_add_f32_e32 v91, v113, v91
	v_add_f32_e32 v115, v113, v84
	v_add_f32_e32 v155, v113, v85
	v_add_f32_e32 v86, v113, v86
	v_add_f32_e32 v87, v113, v87
	v_add_f32_e32 v159, v113, v81
	v_add_f32_e32 v160, v113, v82
	v_add_f32_e32 v113, v113, v83
	v_lshlrev_b64 v[82:83], 13, v[118:119]
	v_ashrrev_i32_e32 v81, 31, v80
	v_lshl_add_u64 v[82:83], s[56:57], 0, v[82:83]
	v_lshlrev_b64 v[84:85], 12, v[80:81]
	v_lshl_add_u64 v[82:83], v[82:83], 0, v[100:101]
	v_lshl_add_u64 v[84:85], s[58:59], 0, v[84:85]
	v_lshl_add_u64 v[84:85], v[84:85], 0, v[100:101]
	s_waitcnt vmcnt(18)
	v_add_f32_e32 v76, v111, v76
	v_add_f32_e32 v77, v111, v77
	v_add_f32_e32 v78, v111, v78
	v_add_f32_e32 v79, v111, v79
	v_add_f32_e32 v72, v111, v72
	v_add_f32_e32 v73, v111, v73
	v_add_f32_e32 v74, v111, v74
	v_add_f32_e32 v75, v111, v75
	v_add_f32_e32 v70, v111, v70
	v_add_f32_e32 v71, v111, v71
	s_waitcnt vmcnt(17)
	v_add_f32_e32 v60, v109, v60
	v_add_f32_e32 v61, v109, v61
	v_add_f32_e32 v56, v109, v56
	v_add_f32_e32 v57, v109, v57
	v_add_f32_e32 v58, v109, v58
	v_add_f32_e32 v59, v109, v59
	v_add_f32_e32 v62, v109, v62
	v_add_f32_e32 v63, v109, v63
	v_add_f32_e32 v54, v109, v54
	v_add_f32_e32 v55, v109, v55
	s_add_i32 s50, s50, s45
	s_waitcnt vmcnt(16)
	v_add_f32_e32 v44, v107, v44
	v_add_f32_e32 v45, v107, v45
	v_add_f32_e32 v46, v107, v46
	v_add_f32_e32 v47, v107, v47
	v_add_f32_e32 v40, v107, v40
	v_add_f32_e32 v41, v107, v41
	v_add_f32_e32 v39, v107, v39
	v_add_f32_e32 v34, v107, v34
	v_add_f32_e32 v35, v107, v35
	s_add_i32 s28, s28, s29
	s_add_i32 s34, s34, s35
	s_add_i32 s3, s48, s50
	v_add_f32_e32 v42, v107, v42
	v_add_f32_e32 v43, v107, v43
	v_add_f32_e32 v36, v107, v36
	v_add_f32_e32 v37, v107, v37
	v_add_f32_e32 v38, v107, v38
	s_cmpk_lt_i32 s3, 0x200
	s_waitcnt vmcnt(15)
	v_lshlrev_b32_e32 v119, 16, v138
	s_waitcnt vmcnt(14)
	v_lshlrev_b32_e32 v162, 16, v152
	v_and_b32_e32 v152, 0xffff0000, v152
	v_and_b32_e32 v138, 0xffff0000, v138
	v_lshlrev_b32_e32 v161, 16, v139
	v_and_b32_e32 v139, 0xffff0000, v139
	v_lshlrev_b32_e32 v163, 16, v153
	v_and_b32_e32 v153, 0xffff0000, v153
	s_waitcnt vmcnt(13)
	v_lshlrev_b32_e32 v165, 16, v157
	v_and_b32_e32 v157, 0xffff0000, v157
	v_mul_f32_e32 v88, v88, v162
	v_mul_f32_e32 v89, v89, v152
	v_lshlrev_b32_e32 v164, 16, v156
	v_and_b32_e32 v156, 0xffff0000, v156
	v_mul_f32_e32 v92, v92, v119
	v_mul_f32_e32 v93, v93, v138
	v_mul_f32_e32 v94, v94, v161
	v_mul_f32_e32 v95, v95, v139
	v_mul_f32_e32 v90, v90, v163
	v_mul_f32_e32 v91, v91, v153
	v_mul_f32_e32 v138, v86, v165
	v_mul_f32_e32 v139, v87, v157
	v_cvt_pk_bf16_f32 v86, v92, v93
	v_cvt_pk_bf16_f32 v87, v94, v95
	global_store_dwordx2 v[82:83], v[86:87], off sc1
	v_cvt_pk_bf16_f32 v88, v88, v89
	v_cvt_pk_bf16_f32 v89, v90, v91
	global_store_dwordx2 v[82:83], v[88:89], off offset:32 sc1
	s_waitcnt vmcnt(14)
	v_lshlrev_b32_e32 v166, 16, v136
	v_and_b32_e32 v136, 0xffff0000, v136
	v_lshlrev_b32_e32 v167, 16, v137
	v_and_b32_e32 v137, 0xffff0000, v137
	v_mul_f32_e32 v115, v115, v164
	v_mul_f32_e32 v119, v155, v156
	s_waitcnt vmcnt(10)
	s_nop 1
	v_mov_b64_e32 v[86:87], v[196:197]
	s_nop 1
	v_mov_b64_e32 v[88:89], v[198:199]
	v_cvt_pk_bf16_f32 v90, v115, v119
	v_cvt_pk_bf16_f32 v91, v138, v139
	global_store_dwordx2 v[82:83], v[90:91], off offset:64 sc1
	v_mul_f32_e32 v152, v158, v166
	v_mul_f32_e32 v136, v159, v136
	v_mul_f32_e32 v153, v160, v167
	v_mul_f32_e32 v113, v113, v137
	s_nop 1
	v_mov_b64_e32 v[90:91], v[200:201]
	v_cvt_pk_bf16_f32 v92, v152, v136
	v_cvt_pk_bf16_f32 v93, v153, v113
	global_store_dwordx2 v[82:83], v[92:93], off offset:96 sc1
	s_nop 1
	v_mov_b64_e32 v[82:83], v[202:203]
	v_add_f32_e32 v92, v111, v64
	v_or_b32_e32 v64, 32, v118
	v_add_f32_e32 v93, v111, v65
	v_add_f32_e32 v94, v111, v66
	v_add_f32_e32 v95, v111, v67
	v_ashrrev_i32_e32 v65, 31, v64
	v_lshlrev_b64 v[66:67], 13, v[80:81]
	v_add_f32_e32 v84, v111, v68
	v_add_f32_e32 v85, v111, v69
	v_lshlrev_b64 v[68:69], 12, v[64:65]
	v_lshl_add_u64 v[66:67], s[56:57], 0, v[66:67]
	v_lshl_add_u64 v[68:69], s[58:59], 0, v[68:69]
	v_lshl_add_u64 v[66:67], v[66:67], 0, v[100:101]
	v_lshl_add_u64 v[68:69], v[68:69], 0, v[100:101]
	s_nop 0
	v_lshlrev_b32_e32 v80, 16, v86
	s_nop 0
	v_lshlrev_b32_e32 v111, 16, v88
	v_and_b32_e32 v88, 0xffff0000, v88
	v_and_b32_e32 v81, 0xffff0000, v86
	v_lshlrev_b32_e32 v86, 16, v87
	v_and_b32_e32 v87, 0xffff0000, v87
	v_lshlrev_b32_e32 v113, 16, v89
	v_and_b32_e32 v89, 0xffff0000, v89
	v_mul_f32_e32 v72, v72, v111
	s_nop 0
	v_lshlrev_b32_e32 v115, 16, v90
	v_and_b32_e32 v90, 0xffff0000, v90
	v_lshlrev_b32_e32 v119, 16, v91
	v_and_b32_e32 v91, 0xffff0000, v91
	v_mul_f32_e32 v73, v73, v88
	s_nop 0
	v_lshlrev_b32_e32 v136, 16, v82
	v_and_b32_e32 v82, 0xffff0000, v82
	v_lshlrev_b32_e32 v137, 16, v83
	v_and_b32_e32 v83, 0xffff0000, v83
	v_mul_f32_e32 v76, v76, v80
	v_mul_f32_e32 v77, v77, v81
	v_mul_f32_e32 v78, v78, v86
	v_mul_f32_e32 v79, v79, v87
	v_mul_f32_e32 v74, v74, v113
	v_mul_f32_e32 v75, v75, v89
	v_mul_f32_e32 v80, v84, v115
	v_mul_f32_e32 v81, v85, v90
	v_mul_f32_e32 v84, v70, v119
	v_mul_f32_e32 v85, v71, v91
	v_cvt_pk_bf16_f32 v70, v76, v77
	v_cvt_pk_bf16_f32 v71, v78, v79
	global_store_dwordx2 v[66:67], v[70:71], off sc1
	v_cvt_pk_bf16_f32 v72, v72, v73
	v_cvt_pk_bf16_f32 v73, v74, v75
	global_store_dwordx2 v[66:67], v[72:73], off offset:32 sc1
	v_mul_f32_e32 v86, v92, v136
	v_mul_f32_e32 v82, v93, v82
	v_mul_f32_e32 v87, v94, v137
	v_mul_f32_e32 v83, v95, v83
	s_waitcnt vmcnt(10)
	s_nop 1
	v_mov_b64_e32 v[70:71], v[204:205]
	s_nop 1
	v_mov_b64_e32 v[72:73], v[206:207]
	v_cvt_pk_bf16_f32 v74, v80, v81
	v_cvt_pk_bf16_f32 v75, v84, v85
	global_store_dwordx2 v[66:67], v[74:75], off offset:64 sc1
	v_cvt_pk_bf16_f32 v76, v86, v82
	v_cvt_pk_bf16_f32 v77, v87, v83
	global_store_dwordx2 v[66:67], v[76:77], off offset:96 sc1
	s_nop 1
	v_mov_b64_e32 v[74:75], v[208:209]
	v_add_f32_e32 v76, v109, v48
	s_nop 1
	v_mov_b64_e32 v[66:67], v[226:227]
	v_or_b32_e32 v48, 48, v118
	v_add_f32_e32 v77, v109, v49
	v_add_f32_e32 v78, v109, v50
	v_add_f32_e32 v79, v109, v51
	v_ashrrev_i32_e32 v49, 31, v48
	v_lshlrev_b64 v[50:51], 13, v[64:65]
	v_add_f32_e32 v68, v109, v52
	v_add_f32_e32 v69, v109, v53
	v_lshlrev_b64 v[52:53], 12, v[48:49]
	v_lshl_add_u64 v[50:51], s[56:57], 0, v[50:51]
	v_lshl_add_u64 v[52:53], s[58:59], 0, v[52:53]
	v_lshl_add_u64 v[50:51], v[50:51], 0, v[100:101]
	v_lshl_add_u64 v[52:53], v[52:53], 0, v[100:101]
	s_nop 0
	v_lshlrev_b32_e32 v64, 16, v70
	v_and_b32_e32 v65, 0xffff0000, v70
	s_nop 0
	v_lshlrev_b32_e32 v80, 16, v72
	v_and_b32_e32 v72, 0xffff0000, v72
	v_lshlrev_b32_e32 v81, 16, v73
	v_and_b32_e32 v73, 0xffff0000, v73
	v_lshlrev_b32_e32 v70, 16, v71
	v_and_b32_e32 v71, 0xffff0000, v71
	s_nop 0
	v_lshlrev_b32_e32 v82, 16, v74
	v_and_b32_e32 v74, 0xffff0000, v74
	v_lshlrev_b32_e32 v83, 16, v75
	v_and_b32_e32 v75, 0xffff0000, v75
	s_nop 0
	v_lshlrev_b32_e32 v84, 16, v66
	v_and_b32_e32 v66, 0xffff0000, v66
	v_lshlrev_b32_e32 v85, 16, v67
	v_and_b32_e32 v67, 0xffff0000, v67
	v_mul_f32_e32 v60, v60, v64
	v_mul_f32_e32 v61, v61, v65
	v_mul_f32_e32 v56, v56, v80
	v_mul_f32_e32 v57, v57, v72
	v_mul_f32_e32 v58, v58, v81
	v_mul_f32_e32 v59, v59, v73
	v_mul_f32_e32 v62, v62, v70
	v_mul_f32_e32 v63, v63, v71
	v_mul_f32_e32 v64, v68, v82
	v_mul_f32_e32 v65, v69, v74
	v_mul_f32_e32 v68, v54, v83
	v_mul_f32_e32 v69, v55, v75
	v_mul_f32_e32 v70, v76, v84
	v_mul_f32_e32 v66, v77, v66
	v_mul_f32_e32 v71, v78, v85
	v_mul_f32_e32 v67, v79, v67
	v_cvt_pk_bf16_f32 v54, v60, v61
	v_cvt_pk_bf16_f32 v55, v62, v63
	global_store_dwordx2 v[50:51], v[54:55], off sc1
	v_cvt_pk_bf16_f32 v56, v56, v57
	v_cvt_pk_bf16_f32 v57, v58, v59
	global_store_dwordx2 v[50:51], v[56:57], off offset:32 sc1
	v_cvt_pk_bf16_f32 v58, v64, v65
	v_cvt_pk_bf16_f32 v59, v68, v69
	global_store_dwordx2 v[50:51], v[58:59], off offset:64 sc1
	v_cvt_pk_bf16_f32 v60, v70, v66
	v_cvt_pk_bf16_f32 v61, v71, v67
	global_store_dwordx2 v[50:51], v[60:61], off offset:96 sc1
	s_waitcnt vmcnt(12)
	s_nop 1
	v_mov_b64_e32 v[54:55], v[228:229]
	s_nop 1
	v_mov_b64_e32 v[56:57], v[230:231]
	s_nop 1
	v_mov_b64_e32 v[58:59], v[232:233]
	s_nop 0
	s_nop 1
	v_mov_b64_e32 v[50:51], v[234:235]
	v_add_f32_e32 v52, v107, v32
	v_add_f32_e32 v53, v107, v33
	v_lshlrev_b64 v[32:33], 13, v[48:49]
	v_lshl_add_u64 v[32:33], s[56:57], 0, v[32:33]
	v_lshl_add_u64 v[32:33], v[32:33], 0, v[100:101]
	s_nop 0
	v_lshlrev_b32_e32 v48, 16, v54
	v_and_b32_e32 v49, 0xffff0000, v54
	v_lshlrev_b32_e32 v54, 16, v55
	v_and_b32_e32 v55, 0xffff0000, v55
	s_nop 0
	v_lshlrev_b32_e32 v60, 16, v56
	v_and_b32_e32 v56, 0xffff0000, v56
	s_nop 0
	v_lshlrev_b32_e32 v63, 16, v59
	v_and_b32_e32 v59, 0xffff0000, v59
	s_nop 0
	v_lshlrev_b32_e32 v64, 16, v50
	v_and_b32_e32 v50, 0xffff0000, v50
	v_lshlrev_b32_e32 v65, 16, v51
	v_and_b32_e32 v51, 0xffff0000, v51
	v_lshlrev_b32_e32 v61, 16, v57
	v_and_b32_e32 v57, 0xffff0000, v57
	v_lshlrev_b32_e32 v62, 16, v58
	v_and_b32_e32 v58, 0xffff0000, v58
	v_mul_f32_e32 v44, v44, v48
	v_mul_f32_e32 v45, v45, v49
	v_mul_f32_e32 v46, v46, v54
	v_mul_f32_e32 v47, v47, v55
	v_mul_f32_e32 v40, v40, v60
	v_mul_f32_e32 v41, v41, v56
	v_mul_f32_e32 v39, v39, v59
	v_mul_f32_e32 v50, v53, v50
	v_mul_f32_e32 v53, v34, v65
	v_mul_f32_e32 v51, v35, v51
	v_cvt_pk_bf16_f32 v34, v44, v45
	v_cvt_pk_bf16_f32 v35, v46, v47
	v_mul_f32_e32 v42, v42, v61
	v_mul_f32_e32 v43, v43, v57
	v_mul_f32_e32 v48, v36, v62
	v_mul_f32_e32 v49, v37, v58
	v_mul_f32_e32 v54, v38, v63
	v_mul_f32_e32 v52, v52, v64
	v_cvt_pk_bf16_f32 v36, v40, v41
	v_cvt_pk_bf16_f32 v37, v42, v43
	v_cvt_pk_bf16_f32 v38, v48, v49
	v_cvt_pk_bf16_f32 v39, v54, v39
	v_cvt_pk_bf16_f32 v40, v52, v50
	v_cvt_pk_bf16_f32 v41, v53, v51
	global_store_dwordx2 v[32:33], v[34:35], off sc1
	global_store_dwordx2 v[32:33], v[36:37], off offset:32 sc1
	global_store_dwordx2 v[32:33], v[38:39], off offset:64 sc1
	global_store_dwordx2 v[32:33], v[40:41], off offset:96 sc1
	s_barrier
	s_cbranch_scc0 .LBB0_453

.Ls5p_swap:
	v_permlane32_swap_b32_e32 v0, v112
	v_permlane32_swap_b32_e32 v1, v113
	v_permlane32_swap_b32_e32 v2, v114
	v_permlane32_swap_b32_e32 v3, v115
	v_permlane32_swap_b32_e32 v4, v116
	v_permlane32_swap_b32_e32 v5, v117
	v_permlane32_swap_b32_e32 v6, v118
	v_permlane32_swap_b32_e32 v7, v119
	v_permlane32_swap_b32_e32 v8, v120
	v_permlane32_swap_b32_e32 v9, v121
	v_permlane32_swap_b32_e32 v10, v122
	v_permlane32_swap_b32_e32 v11, v123
	v_permlane32_swap_b32_e32 v12, v124
	v_permlane32_swap_b32_e32 v13, v125
	v_permlane32_swap_b32_e32 v14, v126
	v_permlane32_swap_b32_e32 v15, v127
	v_permlane32_swap_b32_e32 v16, v160
	v_permlane32_swap_b32_e32 v17, v161
	v_permlane32_swap_b32_e32 v18, v162
	v_permlane32_swap_b32_e32 v19, v163
	v_permlane32_swap_b32_e32 v20, v164
	v_permlane32_swap_b32_e32 v21, v165
	v_permlane32_swap_b32_e32 v22, v166
	v_permlane32_swap_b32_e32 v23, v167
	v_permlane32_swap_b32_e32 v24, v168
	v_permlane32_swap_b32_e32 v25, v169
	v_permlane32_swap_b32_e32 v26, v170
	v_permlane32_swap_b32_e32 v27, v171
	v_permlane32_swap_b32_e32 v28, v172
	v_permlane32_swap_b32_e32 v29, v173
	v_permlane32_swap_b32_e32 v30, v174
	v_permlane32_swap_b32_e32 v31, v175
	v_fmac_f32_e32 v0, v80, v103
	v_fmac_f32_e32 v16, v80, v102
	v_fmac_f32_e32 v0, v89, v102
	v_fmac_f32_e32 v16, v81, v103
	v_fmac_f32_e32 v1, v80, v0
	v_fmac_f32_e32 v17, v80, v16
	v_cvt_pk_bf16_f32 v134, v0, v16
	v_fmac_f32_e32 v1, v89, v16
	v_fmac_f32_e32 v17, v81, v0
	v_fmac_f32_e32 v2, v80, v1
	v_fmac_f32_e32 v18, v80, v17
	v_cvt_pk_bf16_f32 v135, v1, v17
	v_fmac_f32_e32 v2, v89, v17
	v_fmac_f32_e32 v18, v81, v1
	ds_write_b32 v107, v134
	v_fmac_f32_e32 v3, v80, v2
	v_fmac_f32_e32 v19, v80, v18
	v_cvt_pk_bf16_f32 v136, v2, v18
	v_fmac_f32_e32 v3, v89, v18
	v_fmac_f32_e32 v19, v81, v2
	ds_write_b32 v107, v135 offset:528
	v_fmac_f32_e32 v112, v80, v3
	v_fmac_f32_e32 v160, v80, v19
	v_cvt_pk_bf16_f32 v137, v3, v19
	v_fmac_f32_e32 v112, v89, v19
	v_fmac_f32_e32 v160, v81, v3
	ds_write_b32 v107, v136 offset:1056
	v_fmac_f32_e32 v113, v80, v112
	v_fmac_f32_e32 v161, v80, v160
	v_cvt_pk_bf16_f32 v138, v112, v160
	v_fmac_f32_e32 v113, v89, v160
	v_fmac_f32_e32 v161, v81, v112
	ds_write_b32 v107, v137 offset:1584
	v_fmac_f32_e32 v114, v80, v113
	v_fmac_f32_e32 v162, v80, v161
	v_cvt_pk_bf16_f32 v139, v113, v161
	v_fmac_f32_e32 v114, v89, v161
	v_fmac_f32_e32 v162, v81, v113
	ds_write_b32 v107, v138 offset:2112
	v_fmac_f32_e32 v115, v80, v114
	v_fmac_f32_e32 v163, v80, v162
	v_cvt_pk_bf16_f32 v134, v114, v162
	v_fmac_f32_e32 v115, v89, v162
	v_fmac_f32_e32 v163, v81, v114
	ds_write_b32 v107, v139 offset:2640
	v_fmac_f32_e32 v4, v80, v115
	v_fmac_f32_e32 v20, v80, v163
	v_cvt_pk_bf16_f32 v135, v115, v163
	v_fmac_f32_e32 v4, v89, v163
	v_fmac_f32_e32 v20, v81, v115
	ds_write_b32 v107, v134 offset:3168
	v_fmac_f32_e32 v5, v80, v4
	v_fmac_f32_e32 v21, v80, v20
	v_cvt_pk_bf16_f32 v136, v4, v20
	v_fmac_f32_e32 v5, v89, v20
	v_fmac_f32_e32 v21, v81, v4
	ds_write_b32 v107, v135 offset:3696
	v_fmac_f32_e32 v6, v80, v5
	v_fmac_f32_e32 v22, v80, v21
	v_cvt_pk_bf16_f32 v137, v5, v21
	v_fmac_f32_e32 v6, v89, v21
	v_fmac_f32_e32 v22, v81, v5
	ds_write_b32 v107, v136 offset:4224
	v_fmac_f32_e32 v7, v80, v6
	v_fmac_f32_e32 v23, v80, v22
	v_cvt_pk_bf16_f32 v138, v6, v22
	v_fmac_f32_e32 v7, v89, v22
	v_fmac_f32_e32 v23, v81, v6
	ds_write_b32 v107, v137 offset:4752
	v_fmac_f32_e32 v116, v80, v7
	v_fmac_f32_e32 v164, v80, v23
	v_cvt_pk_bf16_f32 v139, v7, v23
	v_fmac_f32_e32 v116, v89, v23
	v_fmac_f32_e32 v164, v81, v7
	ds_write_b32 v107, v138 offset:5280
	v_fmac_f32_e32 v117, v80, v116
	v_fmac_f32_e32 v165, v80, v164
	v_cvt_pk_bf16_f32 v134, v116, v164
	v_fmac_f32_e32 v117, v89, v164
	v_fmac_f32_e32 v165, v81, v116
	ds_write_b32 v107, v139 offset:5808
	v_fmac_f32_e32 v118, v80, v117
	v_fmac_f32_e32 v166, v80, v165
	v_cvt_pk_bf16_f32 v135, v117, v165
	v_fmac_f32_e32 v118, v89, v165
	v_fmac_f32_e32 v166, v81, v117
	ds_write_b32 v107, v134 offset:6336
	v_fmac_f32_e32 v119, v80, v118
	v_fmac_f32_e32 v167, v80, v166
	v_cvt_pk_bf16_f32 v136, v118, v166
	v_fmac_f32_e32 v119, v89, v166
	v_fmac_f32_e32 v167, v81, v118
	ds_write_b32 v107, v135 offset:6864
	v_fmac_f32_e32 v8, v80, v119
	v_fmac_f32_e32 v24, v80, v167
	v_cvt_pk_bf16_f32 v137, v119, v167
	v_fmac_f32_e32 v8, v89, v167
	v_fmac_f32_e32 v24, v81, v119
	ds_write_b32 v107, v136 offset:7392
	v_fmac_f32_e32 v9, v80, v8
	v_fmac_f32_e32 v25, v80, v24
	v_cvt_pk_bf16_f32 v138, v8, v24
	v_fmac_f32_e32 v9, v89, v24
	v_fmac_f32_e32 v25, v81, v8
	ds_write_b32 v107, v137 offset:7920
	ds_read_b128 v[194:197], v108
	ds_read_b128 v[198:201], v108 offset:64
	ds_read_b128 v[202:205], v108 offset:128
	ds_read_b128 v[206:209], v108 offset:192
	v_fmac_f32_e32 v10, v80, v9
	v_fmac_f32_e32 v26, v80, v25
	v_cvt_pk_bf16_f32 v139, v9, v25
	v_fmac_f32_e32 v10, v89, v25
	v_fmac_f32_e32 v26, v81, v9
	ds_write_b32 v107, v138 offset:8448
	v_fmac_f32_e32 v11, v80, v10
	v_fmac_f32_e32 v27, v80, v26
	v_cvt_pk_bf16_f32 v134, v10, v26
	v_fmac_f32_e32 v11, v89, v26
	v_fmac_f32_e32 v27, v81, v10
	ds_write_b32 v107, v139 offset:8976
	v_fmac_f32_e32 v120, v80, v11
	v_fmac_f32_e32 v168, v80, v27
	v_cvt_pk_bf16_f32 v135, v11, v27
	v_fmac_f32_e32 v120, v89, v27
	v_fmac_f32_e32 v168, v81, v11
	ds_write_b32 v107, v134 offset:9504
	v_fmac_f32_e32 v121, v80, v120
	v_fmac_f32_e32 v169, v80, v168
	v_cvt_pk_bf16_f32 v136, v120, v168
	v_fmac_f32_e32 v121, v89, v168
	v_fmac_f32_e32 v169, v81, v120
	ds_write_b32 v107, v135 offset:10032
	v_fmac_f32_e32 v122, v80, v121
	v_fmac_f32_e32 v170, v80, v169
	v_cvt_pk_bf16_f32 v137, v121, v169
	v_fmac_f32_e32 v122, v89, v169
	v_fmac_f32_e32 v170, v81, v121
	ds_write_b32 v107, v136 offset:10560
	s_waitcnt lgkmcnt(5)
	v_mfma_f32_16x16x32_bf16 v[226:229], v[48:51], v[194:197], 0
	v_fmac_f32_e32 v123, v80, v122
	v_fmac_f32_e32 v171, v80, v170
	v_cvt_pk_bf16_f32 v138, v122, v170
	v_fmac_f32_e32 v123, v89, v170
	v_fmac_f32_e32 v171, v81, v122
	ds_write_b32 v107, v137 offset:11088
	v_mfma_f32_16x16x32_bf16 v[226:229], v[52:55], v[198:201], v[226:229]
	v_fmac_f32_e32 v12, v80, v123
	v_fmac_f32_e32 v28, v80, v171
	v_cvt_pk_bf16_f32 v139, v123, v171
	v_fmac_f32_e32 v12, v89, v171
	v_fmac_f32_e32 v28, v81, v123
	ds_write_b32 v107, v138 offset:11616
	v_mfma_f32_16x16x32_bf16 v[226:229], v[56:59], v[202:205], v[226:229]
	v_fmac_f32_e32 v13, v80, v12
	v_fmac_f32_e32 v29, v80, v28
	v_cvt_pk_bf16_f32 v134, v12, v28
	v_fmac_f32_e32 v13, v89, v28
	v_fmac_f32_e32 v29, v81, v12
	ds_write_b32 v107, v139 offset:12144
	v_mfma_f32_16x16x32_bf16 v[226:229], v[60:63], v[206:209], v[226:229]
	v_fmac_f32_e32 v14, v80, v13
	v_fmac_f32_e32 v30, v80, v29
	v_cvt_pk_bf16_f32 v135, v13, v29
	v_fmac_f32_e32 v14, v89, v29
	v_fmac_f32_e32 v30, v81, v13
	ds_write_b32 v107, v134 offset:12672
	v_fmac_f32_e32 v15, v80, v14
	v_fmac_f32_e32 v31, v80, v30
	v_cvt_pk_bf16_f32 v136, v14, v30
	v_fmac_f32_e32 v15, v89, v30
	v_fmac_f32_e32 v31, v81, v14
	ds_write_b32 v107, v135 offset:13200
	v_fmac_f32_e32 v124, v80, v15
	v_fmac_f32_e32 v172, v80, v31
	v_cvt_pk_bf16_f32 v137, v15, v31
	v_fmac_f32_e32 v124, v89, v31
	v_fmac_f32_e32 v172, v81, v15
	ds_write_b32 v107, v136 offset:13728
	v_fmac_f32_e32 v125, v80, v124
	v_fmac_f32_e32 v173, v80, v172
	v_cvt_pk_bf16_f32 v138, v124, v172
	v_fmac_f32_e32 v125, v89, v172
	v_fmac_f32_e32 v173, v81, v124
	ds_write_b32 v107, v137 offset:14256
	v_fmac_f32_e32 v126, v80, v125
	v_fmac_f32_e32 v174, v80, v173
	v_cvt_pk_bf16_f32 v139, v125, v173
	v_fmac_f32_e32 v126, v89, v173
	v_fmac_f32_e32 v174, v81, v125
	ds_write_b32 v107, v138 offset:14784
	v_fma_f32 v103, v80, v126, v127
	v_fma_f32 v102, v80, v174, v175
	v_cvt_pk_bf16_f32 v134, v126, v174
	v_fmac_f32_e32 v103, v89, v174
	v_fmac_f32_e32 v102, v81, v126
	ds_write_b32 v107, v139 offset:15312
	v_cvt_pk_bf16_f32 v135, v103, v102
	ds_write_b32 v107, v134 offset:15840
	ds_write_b32 v107, v135 offset:16368
	v_mov_b64_e32 v[18:19], s[16:17]
	ds_read_b128 v[194:197], v108 offset:8448
	ds_read_b128 v[198:201], v108 offset:8512
	ds_read_b128 v[202:205], v108 offset:8576
	ds_read_b128 v[206:209], v108 offset:8640
	v_lshlrev_b32_e32 v10, 16, v100
	v_and_b32_e32 v11, 0xffff0000, v100
	v_pk_fma_f32 v[14:15], v[64:65], v[10:11], v[226:227]
	s_nop 0
	v_pk_mul_f32 v[6:7], v[14:15], v[14:15]
	s_nop 0
	v_pk_fma_f32 v[6:7], v[6:7], s[10:11], v[18:19] op_sel_hi:[1,0,0] neg_lo:[1,0,0] neg_hi:[1,0,0]
	s_nop 0
	v_pk_mul_f32 v[6:7], v[14:15], v[6:7]
	s_nop 0
	v_exp_f32_e32 v6, v6
	v_exp_f32_e32 v7, v7
	s_nop 0
	v_pk_add_f32 v[10:11], v[6:7], 1.0 op_sel_hi:[1,0]
	v_lshlrev_b32_e32 v6, 16, v101
	v_and_b32_e32 v7, 0xffff0000, v101
	v_pk_fma_f32 v[20:21], v[66:67], v[6:7], v[228:229]
	v_rcp_f32_e32 v16, v10
	v_pk_mul_f32 v[6:7], v[20:21], v[20:21]
	v_rcp_f32_e32 v17, v11
	v_pk_fma_f32 v[6:7], v[6:7], s[10:11], v[18:19] op_sel_hi:[1,0,0] neg_lo:[1,0,0] neg_hi:[1,0,0]
	s_nop 0
	s_nop 0
	v_pk_mul_f32 v[6:7], v[20:21], v[6:7]
	v_pk_mul_f32 v[24:25], v[14:15], v[16:17]
	v_exp_f32_e32 v12, v6
	v_exp_f32_e32 v13, v7
	s_nop 0
	v_pk_add_f32 v[22:23], v[12:13], 1.0 op_sel_hi:[1,0]
	s_waitcnt lgkmcnt(3)
	v_mfma_f32_16x16x32_bf16 v[6:9], v[48:51], v[194:197], 0
	v_rcp_f32_e32 v22, v22
	v_rcp_f32_e32 v23, v23
	s_waitcnt lgkmcnt(2)
	v_mfma_f32_16x16x32_bf16 v[6:9], v[52:55], v[198:201], v[6:9]
	v_pk_mul_f32 v[20:21], v[20:21], v[22:23]
	v_cvt_pk_bf16_f32 v22, v24, v25
	s_waitcnt lgkmcnt(1)
	v_mfma_f32_16x16x32_bf16 v[6:9], v[56:59], v[202:205], v[6:9]
	s_waitcnt lgkmcnt(0)
	v_mfma_f32_16x16x32_bf16 v[6:9], v[60:63], v[206:209], v[6:9]
	v_lshlrev_b32_e32 v10, 16, v94
	v_and_b32_e32 v11, 0xffff0000, v94
	v_lshlrev_b32_e32 v12, 16, v95
	v_and_b32_e32 v13, 0xffff0000, v95
	s_nop 3
	v_pk_fma_f32 v[6:7], v[64:65], v[10:11], v[6:7]
	v_pk_fma_f32 v[8:9], v[66:67], v[12:13], v[8:9]
	v_pk_mul_f32 v[10:11], v[6:7], v[6:7]
	v_pk_mul_f32 v[12:13], v[8:9], v[8:9]
	v_pk_fma_f32 v[10:11], v[10:11], s[10:11], v[18:19] op_sel_hi:[1,0,0] neg_lo:[1,0,0] neg_hi:[1,0,0]
	v_pk_fma_f32 v[12:13], v[12:13], s[10:11], v[18:19] op_sel_hi:[1,0,0] neg_lo:[1,0,0] neg_hi:[1,0,0]
	v_pk_mul_f32 v[10:11], v[6:7], v[10:11]
	v_pk_mul_f32 v[12:13], v[8:9], v[12:13]
	v_exp_f32_e32 v10, v10
	v_exp_f32_e32 v11, v11
	v_exp_f32_e32 v12, v12
	v_exp_f32_e32 v13, v13
	v_pk_add_f32 v[10:11], v[10:11], 1.0 op_sel_hi:[1,0]
	v_rcp_f32_e32 v10, v10
	v_rcp_f32_e32 v11, v11
	v_pk_add_f32 v[12:13], v[12:13], 1.0 op_sel_hi:[1,0]
	v_cvt_pk_bf16_f32 v23, v20, v21
	global_store_dwordx2 v[236:237], v[22:23], off sc1
	v_rcp_f32_e32 v12, v12
	v_rcp_f32_e32 v13, v13
	v_pk_mul_f32 v[6:7], v[6:7], v[10:11]
	s_nop 0
	s_nop 0
	v_cvt_pk_bf16_f32 v6, v6, v7
	v_pk_mul_f32 v[8:9], v[8:9], v[12:13]
	s_nop 0
	v_cvt_pk_bf16_f32 v7, v8, v9
	global_store_dwordx2 v[238:239], v[6:7], off sc1
	v_lshl_add_u64 v[236:237], v[236:237], 0, s[50:51]
	v_lshl_add_u64 v[238:239], v[238:239], 0, s[50:51]
	s_add_i32 s5, s5, 32
	s_add_i32 s6, s6, 1
	s_waitcnt vmcnt(2)
	v_mov_b64_e32 v[100:101], v[190:191]
	v_mov_b64_e32 v[94:95], v[192:193]
	s_cmp_lt_u32 s6, 64
	s_cbranch_scc1 .Ls5p_tile
	s_branch .LBB0_463
